# rownorm: nt row loads, bf16 output stores back to default write-back policy (sc1 removed)
# baseline (speedup 1.0000x reference)
.LBB0_388:
	v_add_u32_e32 v0, s18, v58
	v_cmp_gt_i32_e64 s[8:9], s3, v0
	v_lshrrev_b32_e32 v69, 3, v58
	v_and_b32_e32 v59, 0x700, v66
	v_cndmask_b32_e64 v1, v58, v0, s[8:9]
	v_lshlrev_b32_e32 v2, 5, v1
	v_lshrrev_b32_e32 v3, 3, v1
	v_and_b32_e32 v2, 0x700, v2
	v_and_b32_e32 v3, 0xf8, v3
	v_and_b32_e32 v4, 0xfffff807, v1
	v_or3_b32 v2, v2, v4, v3
	v_cndmask_b32_e32 v56, v1, v2, vcc
	v_add_u32_e32 v2, s18, v0
	v_cmp_gt_i32_e64 s[4:5], s3, v2
	v_ashrrev_i32_e32 v57, 31, v56
	v_add_u32_e32 v68, s18, v2
	v_cndmask_b32_e64 v3, v58, v2, s[4:5]
	v_lshlrev_b32_e32 v0, 5, v3
	v_and_b32_e32 v4, 0x700, v0
	v_lshlrev_b64 v[0:1], 12, v[56:57]
	v_lshl_add_u64 v[0:1], v[50:51], 0, v[0:1]
	v_lshrrev_b32_e32 v5, 3, v3
	global_load_dwordx4 v[44:47], v[0:1], off nt
	global_load_dwordx4 v[40:43], v[0:1], off offset:1024 nt
	v_and_b32_e32 v5, 0xf8, v5
	v_and_b32_e32 v6, 0xfffff807, v3
	global_load_dwordx4 v[36:39], v[0:1], off offset:2048 nt
	global_load_dwordx4 v[32:35], v[0:1], off offset:3072 nt
	v_or3_b32 v0, v4, v6, v5
	v_cndmask_b32_e32 v54, v3, v0, vcc
	v_ashrrev_i32_e32 v55, 31, v54
	v_lshlrev_b64 v[0:1], 12, v[54:55]
	v_lshl_add_u64 v[0:1], v[50:51], 0, v[0:1]
	v_cmp_gt_i32_e64 s[6:7], s3, v68
	global_load_dwordx4 v[28:31], v[0:1], off nt
	global_load_dwordx4 v[24:27], v[0:1], off offset:1024 nt
	global_load_dwordx4 v[20:23], v[0:1], off offset:2048 nt
	global_load_dwordx4 v[16:19], v[0:1], off offset:3072 nt
	v_cndmask_b32_e64 v0, v58, v68, s[6:7]
	v_lshlrev_b32_e32 v1, 5, v0
	v_lshrrev_b32_e32 v2, 3, v0
	v_and_b32_e32 v3, 0xfffff807, v0
	v_and_b32_e32 v1, 0x700, v1
	v_and_b32_e32 v2, 0xf8, v2
	v_or3_b32 v1, v1, v3, v2
	v_cndmask_b32_e32 v52, v0, v1, vcc
	v_ashrrev_i32_e32 v53, 31, v52
	v_lshlrev_b64 v[0:1], 12, v[52:53]
	v_lshl_add_u64 v[0:1], v[50:51], 0, v[0:1]
	global_load_dwordx4 v[12:15], v[0:1], off nt
	global_load_dwordx4 v[8:11], v[0:1], off offset:1024 nt
	global_load_dwordx4 v[4:7], v[0:1], off offset:2048 nt
	s_nop 0
	global_load_dwordx4 v[0:3], v[0:1], off offset:3072 nt
	s_waitcnt lgkmcnt(0)
	v_and_b32_e32 v70, 0xfffff807, v58
	v_and_b32_e32 v69, 0xf8, v69
	v_or3_b32 v59, v59, v70, v69
	v_cndmask_b32_e32 v58, v58, v59, vcc
	v_ashrrev_i32_e32 v59, 31, v58
	v_lshlrev_b64 v[70:71], 12, v[58:59]
	v_lshl_add_u64 v[70:71], v[50:51], 0, v[70:71]
	global_load_dwordx4 v[76:79], v[70:71], off nt
	global_load_dwordx4 v[80:83], v[70:71], off offset:1024 nt
	global_load_dwordx4 v[84:87], v[70:71], off offset:2048 nt
	global_load_dwordx4 v[88:91], v[70:71], off offset:3072 nt
	v_lshlrev_b64 v[58:59], 11, v[58:59]
	v_lshl_add_u64 v[58:59], v[48:49], 0, v[58:59]
	s_waitcnt vmcnt(15)
	v_pk_mul_f32 v[70:71], v[44:45], v[44:45]
	s_waitcnt vmcnt(14)
	v_pk_mul_f32 v[74:75], v[40:41], v[40:41]
	v_pk_mul_f32 v[72:73], v[46:47], v[46:47]
	v_pk_mul_f32 v[92:93], v[42:43], v[42:43]
	s_waitcnt vmcnt(13)
	v_pk_mul_f32 v[94:95], v[36:37], v[36:37]
	v_add_f32_e32 v69, v74, v75
	v_add_f32_e32 v110, v70, v71
	v_pk_mul_f32 v[96:97], v[38:39], v[38:39]
	s_waitcnt vmcnt(12)
	v_pk_mul_f32 v[98:99], v[32:33], v[32:33]
	v_add_f32_e32 v111, v94, v95
	v_add_f32_e32 v69, v69, v92
	v_add_f32_e32 v72, v110, v72
	v_pk_mul_f32 v[100:101], v[34:35], v[34:35]
	v_add_f32_e32 v112, v98, v99
	v_add_f32_e32 v92, v111, v96
	v_add_f32_e32 v69, v69, v93
	v_add_f32_e32 v72, v72, v73
	v_add_f32_e32 v96, v112, v100
	v_add_f32_e32 v73, v92, v97
	v_add_f32_e32 v69, v72, v69
	v_add_f32_e32 v92, v96, v101
	v_add_f32_e32 v69, v69, v73
	s_waitcnt vmcnt(11)
	v_pk_mul_f32 v[70:71], v[28:29], v[28:29]
	s_waitcnt vmcnt(9)
	v_pk_mul_f32 v[102:103], v[20:21], v[20:21]
	v_add_f32_e32 v69, v69, v92
	v_add_f32_e32 v70, v70, v71
	v_add_f32_e32 v71, v102, v103
	ds_bpermute_b32 v103, v60, v69
	v_pk_mul_f32 v[74:75], v[30:31], v[30:31]
	v_pk_mul_f32 v[94:95], v[24:25], v[24:25]
	v_pk_mul_f32 v[98:99], v[26:27], v[26:27]
	v_add_f32_e32 v94, v94, v95
	v_add_f32_e32 v70, v70, v74
	v_pk_mul_f32 v[104:105], v[22:23], v[22:23]
	v_add_f32_e32 v72, v94, v98
	v_add_f32_e32 v70, v70, v75
	s_waitcnt vmcnt(6)
	v_pk_mul_f32 v[74:75], v[8:9], v[8:9]
	s_waitcnt lgkmcnt(0)
	v_add_f32_e32 v69, v69, v103
	v_add_f32_e32 v72, v72, v99
	v_add_f32_e32 v71, v71, v104
	v_add_f32_e32 v74, v74, v75
	ds_bpermute_b32 v75, v61, v69
	v_pk_mul_f32 v[106:107], v[16:17], v[16:17]
	v_add_f32_e32 v70, v70, v72
	v_add_f32_e32 v71, v71, v105
	v_pk_mul_f32 v[108:109], v[18:19], v[18:19]
	v_add_f32_e32 v70, v70, v71
	v_add_f32_e32 v71, v106, v107
	v_add_f32_e32 v71, v71, v108
	v_add_f32_e32 v71, v71, v109
	v_add_f32_e32 v102, v70, v71
	v_pk_mul_f32 v[70:71], v[12:13], v[12:13]
	s_waitcnt lgkmcnt(0)
	v_add_f32_e32 v69, v69, v75
	v_add_f32_e32 v70, v70, v71
	ds_bpermute_b32 v71, v62, v69
	v_pk_mul_f32 v[72:73], v[14:15], v[14:15]
	v_pk_mul_f32 v[92:93], v[10:11], v[10:11]
	s_waitcnt vmcnt(5)
	v_pk_mul_f32 v[94:95], v[4:5], v[4:5]
	v_pk_mul_f32 v[96:97], v[6:7], v[6:7]
	s_waitcnt lgkmcnt(0)
	v_add_f32_e32 v69, v69, v71
	v_add_f32_e32 v74, v74, v92
	v_add_f32_e32 v70, v70, v72
	v_add_f32_e32 v72, v94, v95
	ds_bpermute_b32 v71, v63, v69
	v_add_f32_e32 v74, v74, v93
	v_add_f32_e32 v70, v70, v73
	v_add_f32_e32 v72, v72, v96
	s_waitcnt vmcnt(4)
	v_pk_mul_f32 v[98:99], v[0:1], v[0:1]
	v_add_f32_e32 v70, v70, v74
	v_add_f32_e32 v72, v72, v97
	v_pk_mul_f32 v[100:101], v[2:3], v[2:3]
	v_add_f32_e32 v96, v70, v72
	v_add_f32_e32 v70, v98, v99
	s_waitcnt vmcnt(3)
	v_mov_b32_e32 v92, v77
	s_waitcnt vmcnt(2)
	v_mov_b32_e32 v93, v81
	v_add_f32_e32 v70, v70, v100
	v_mov_b32_e32 v74, v76
	v_mov_b32_e32 v75, v80
	v_pk_mul_f32 v[92:93], v[92:93], v[92:93]
	v_add_f32_e32 v97, v70, v101
	s_waitcnt lgkmcnt(0)
	v_add_f32_e32 v69, v69, v71
	v_mov_b32_e32 v70, v78
	v_mov_b32_e32 v71, v82
	v_pk_fma_f32 v[74:75], v[74:75], v[74:75], v[92:93]
	s_waitcnt vmcnt(1)
	v_mov_b32_e32 v94, v85
	s_waitcnt vmcnt(0)
	v_mov_b32_e32 v95, v89
	v_mov_b32_e32 v72, v79
	v_mov_b32_e32 v73, v83
	v_pk_fma_f32 v[70:71], v[70:71], v[70:71], v[74:75]
	v_mov_b32_e32 v92, v84
	v_mov_b32_e32 v93, v88
	v_pk_mul_f32 v[94:95], v[94:95], v[94:95]
	v_pk_fma_f32 v[70:71], v[72:73], v[72:73], v[70:71]
	v_mov_b32_e32 v72, v86
	v_mov_b32_e32 v73, v90
	v_pk_fma_f32 v[92:93], v[92:93], v[92:93], v[94:95]
	v_mov_b32_e32 v74, v87
	v_mov_b32_e32 v75, v91
	v_pk_fma_f32 v[72:73], v[72:73], v[72:73], v[92:93]
	v_add_f32_e32 v70, v70, v71
	v_pk_fma_f32 v[72:73], v[74:75], v[74:75], v[72:73]
	ds_bpermute_b32 v74, v60, v102
	v_add_f32_e32 v70, v70, v72
	v_add_f32_e32 v70, v70, v73
	ds_bpermute_b32 v71, v60, v70
	ds_bpermute_b32 v98, v64, v69
	s_waitcnt lgkmcnt(2)
	v_add_f32_e32 v74, v102, v74
	ds_bpermute_b32 v75, v61, v74
	v_add_f32_e32 v72, v96, v97
	s_waitcnt lgkmcnt(2)
	v_add_f32_e32 v70, v70, v71
	ds_bpermute_b32 v71, v61, v70
	s_waitcnt lgkmcnt(2)
	v_add_f32_e32 v73, v69, v98
	ds_bpermute_b32 v69, v60, v72
	s_waitcnt lgkmcnt(2)
	v_add_f32_e32 v74, v74, v75
	ds_bpermute_b32 v75, v62, v74
	s_waitcnt lgkmcnt(2)
	v_add_f32_e32 v70, v70, v71
	ds_bpermute_b32 v71, v62, v70
	s_waitcnt lgkmcnt(2)
	v_add_f32_e32 v69, v72, v69
	ds_bpermute_b32 v72, v61, v69
	s_waitcnt lgkmcnt(2)
	v_add_f32_e32 v74, v74, v75
	ds_bpermute_b32 v75, v63, v74
	s_waitcnt lgkmcnt(2)
	v_add_f32_e32 v70, v70, v71
	ds_bpermute_b32 v71, v63, v70
	s_waitcnt lgkmcnt(2)
	v_add_f32_e32 v69, v69, v72
	ds_bpermute_b32 v72, v62, v69
	s_waitcnt lgkmcnt(2)
	v_add_f32_e32 v75, v74, v75
	ds_bpermute_b32 v92, v64, v75
	s_waitcnt lgkmcnt(2)
	v_add_f32_e32 v70, v70, v71
	ds_bpermute_b32 v71, v64, v70
	s_waitcnt lgkmcnt(2)
	v_add_f32_e32 v69, v69, v72
	ds_bpermute_b32 v72, v63, v69
	ds_bpermute_b32 v74, v65, v73
	s_waitcnt lgkmcnt(2)
	v_add_f32_e32 v70, v70, v71
	ds_bpermute_b32 v94, v65, v70
	v_add_f32_e32 v71, v75, v92
	s_waitcnt lgkmcnt(2)
	v_add_f32_e32 v69, v69, v72
	ds_bpermute_b32 v93, v64, v69
	ds_bpermute_b32 v72, v65, v71
	s_waitcnt lgkmcnt(2)
	v_add_f32_e32 v70, v70, v94
	v_fmamk_f32 v70, v70, 0x3a800000, v67
	v_mul_f32_e32 v75, 0x4b800000, v70
	v_cmp_gt_f32_e64 s[10:11], s22, v70
	s_waitcnt lgkmcnt(1)
	v_add_f32_e32 v69, v69, v93
	v_cndmask_b32_e64 v70, v70, v75, s[10:11]
	v_rsq_f32_e32 v75, v70
	ds_bpermute_b32 v70, v65, v69
	v_mul_f32_e32 v92, 0x45800000, v75
	v_cndmask_b32_e64 v92, v75, v92, s[10:11]
	v_pk_mul_f32 v[76:77], v[76:77], v[92:93] op_sel_hi:[1,0]
	v_pk_mul_f32 v[78:79], v[78:79], v[92:93] op_sel_hi:[1,0]
	v_cvt_pk_bf16_f32 v76, v76, v77
	v_cvt_pk_bf16_f32 v77, v78, v79
	global_store_dwordx2 v[58:59], v[76:77], off
	v_pk_mul_f32 v[76:77], v[80:81], v[92:93] op_sel_hi:[1,0]
	v_pk_mul_f32 v[78:79], v[82:83], v[92:93] op_sel_hi:[1,0]
	v_cvt_pk_bf16_f32 v76, v76, v77
	v_cvt_pk_bf16_f32 v77, v78, v79
	global_store_dwordx2 v[58:59], v[76:77], off offset:512
	v_pk_mul_f32 v[76:77], v[84:85], v[92:93] op_sel_hi:[1,0]
	v_pk_mul_f32 v[78:79], v[86:87], v[92:93] op_sel_hi:[1,0]
	v_cvt_pk_bf16_f32 v76, v76, v77
	v_cvt_pk_bf16_f32 v77, v78, v79
	global_store_dwordx2 v[58:59], v[76:77], off offset:1024
	v_pk_mul_f32 v[76:77], v[88:89], v[92:93] op_sel_hi:[1,0]
	v_pk_mul_f32 v[78:79], v[90:91], v[92:93] op_sel_hi:[1,0]
	v_cvt_pk_bf16_f32 v76, v76, v77
	v_cvt_pk_bf16_f32 v77, v78, v79
	global_store_dwordx2 v[58:59], v[76:77], off offset:1536
	s_and_saveexec_b64 s[10:11], s[8:9]
	s_cbranch_execnz .LBB0_391
	s_or_b64 exec, exec, s[10:11]
	s_and_saveexec_b64 s[8:9], s[4:5]
	s_cbranch_execnz .LBB0_392

.LBB0_868:
	v_add_u32_e32 v0, s16, v58
	v_cmp_gt_i32_e64 s[6:7], s3, v0
	v_lshrrev_b32_e32 v69, 3, v58
	v_and_b32_e32 v59, 0x700, v66
	v_cndmask_b32_e64 v1, v58, v0, s[6:7]
	v_lshlrev_b32_e32 v2, 5, v1
	v_lshrrev_b32_e32 v3, 3, v1
	v_and_b32_e32 v2, 0x700, v2
	v_and_b32_e32 v3, 0xf8, v3
	v_and_b32_e32 v4, 0xfffff807, v1
	v_or3_b32 v2, v2, v4, v3
	v_cndmask_b32_e32 v56, v1, v2, vcc
	v_add_u32_e32 v2, s16, v0
	v_cmp_gt_i32_e64 s[0:1], s3, v2
	v_ashrrev_i32_e32 v57, 31, v56
	v_add_u32_e32 v68, s16, v2
	v_cndmask_b32_e64 v3, v58, v2, s[0:1]
	v_lshlrev_b32_e32 v0, 5, v3
	v_and_b32_e32 v4, 0x700, v0
	v_lshlrev_b64 v[0:1], 12, v[56:57]
	v_lshl_add_u64 v[0:1], v[50:51], 0, v[0:1]
	v_lshrrev_b32_e32 v5, 3, v3
	global_load_dwordx4 v[44:47], v[0:1], off nt
	global_load_dwordx4 v[40:43], v[0:1], off offset:1024 nt
	v_and_b32_e32 v5, 0xf8, v5
	v_and_b32_e32 v6, 0xfffff807, v3
	global_load_dwordx4 v[36:39], v[0:1], off offset:2048 nt
	global_load_dwordx4 v[32:35], v[0:1], off offset:3072 nt
	v_or3_b32 v0, v4, v6, v5
	v_cndmask_b32_e32 v54, v3, v0, vcc
	v_ashrrev_i32_e32 v55, 31, v54
	v_lshlrev_b64 v[0:1], 12, v[54:55]
	v_lshl_add_u64 v[0:1], v[50:51], 0, v[0:1]
	v_cmp_gt_i32_e64 s[4:5], s3, v68
	global_load_dwordx4 v[28:31], v[0:1], off nt
	global_load_dwordx4 v[24:27], v[0:1], off offset:1024 nt
	global_load_dwordx4 v[20:23], v[0:1], off offset:2048 nt
	global_load_dwordx4 v[16:19], v[0:1], off offset:3072 nt
	v_cndmask_b32_e64 v0, v58, v68, s[4:5]
	v_lshlrev_b32_e32 v1, 5, v0
	v_lshrrev_b32_e32 v2, 3, v0
	v_and_b32_e32 v3, 0xfffff807, v0
	v_and_b32_e32 v1, 0x700, v1
	v_and_b32_e32 v2, 0xf8, v2
	v_or3_b32 v1, v1, v3, v2
	v_cndmask_b32_e32 v52, v0, v1, vcc
	v_ashrrev_i32_e32 v53, 31, v52
	v_lshlrev_b64 v[0:1], 12, v[52:53]
	v_lshl_add_u64 v[0:1], v[50:51], 0, v[0:1]
	global_load_dwordx4 v[12:15], v[0:1], off nt
	global_load_dwordx4 v[8:11], v[0:1], off offset:1024 nt
	global_load_dwordx4 v[4:7], v[0:1], off offset:2048 nt
	s_nop 0
	global_load_dwordx4 v[0:3], v[0:1], off offset:3072 nt
	s_waitcnt lgkmcnt(0)
	v_and_b32_e32 v70, 0xfffff807, v58
	v_and_b32_e32 v69, 0xf8, v69
	v_or3_b32 v59, v59, v70, v69
	v_cndmask_b32_e32 v58, v58, v59, vcc
	v_ashrrev_i32_e32 v59, 31, v58
	v_lshlrev_b64 v[70:71], 12, v[58:59]
	v_lshl_add_u64 v[70:71], v[50:51], 0, v[70:71]
	global_load_dwordx4 v[76:79], v[70:71], off nt
	global_load_dwordx4 v[80:83], v[70:71], off offset:1024 nt
	global_load_dwordx4 v[84:87], v[70:71], off offset:2048 nt
	global_load_dwordx4 v[88:91], v[70:71], off offset:3072 nt
	v_lshlrev_b64 v[58:59], 11, v[58:59]
	v_lshl_add_u64 v[58:59], v[48:49], 0, v[58:59]
	s_waitcnt vmcnt(15)
	v_pk_mul_f32 v[70:71], v[44:45], v[44:45]
	s_waitcnt vmcnt(14)
	v_pk_mul_f32 v[74:75], v[40:41], v[40:41]
	v_pk_mul_f32 v[72:73], v[46:47], v[46:47]
	v_pk_mul_f32 v[92:93], v[42:43], v[42:43]
	s_waitcnt vmcnt(13)
	v_pk_mul_f32 v[94:95], v[36:37], v[36:37]
	v_add_f32_e32 v69, v74, v75
	v_add_f32_e32 v110, v70, v71
	v_pk_mul_f32 v[96:97], v[38:39], v[38:39]
	s_waitcnt vmcnt(12)
	v_pk_mul_f32 v[98:99], v[32:33], v[32:33]
	v_add_f32_e32 v111, v94, v95
	v_add_f32_e32 v69, v69, v92
	v_add_f32_e32 v72, v110, v72
	v_pk_mul_f32 v[100:101], v[34:35], v[34:35]
	v_add_f32_e32 v112, v98, v99
	v_add_f32_e32 v92, v111, v96
	v_add_f32_e32 v69, v69, v93
	v_add_f32_e32 v72, v72, v73
	v_add_f32_e32 v96, v112, v100
	v_add_f32_e32 v73, v92, v97
	v_add_f32_e32 v69, v72, v69
	v_add_f32_e32 v92, v96, v101
	v_add_f32_e32 v69, v69, v73
	s_waitcnt vmcnt(11)
	v_pk_mul_f32 v[70:71], v[28:29], v[28:29]
	s_waitcnt vmcnt(9)
	v_pk_mul_f32 v[102:103], v[20:21], v[20:21]
	v_add_f32_e32 v69, v69, v92
	v_add_f32_e32 v70, v70, v71
	v_add_f32_e32 v71, v102, v103
	ds_bpermute_b32 v103, v60, v69
	v_pk_mul_f32 v[74:75], v[30:31], v[30:31]
	v_pk_mul_f32 v[94:95], v[24:25], v[24:25]
	v_pk_mul_f32 v[98:99], v[26:27], v[26:27]
	v_add_f32_e32 v94, v94, v95
	v_add_f32_e32 v70, v70, v74
	v_pk_mul_f32 v[104:105], v[22:23], v[22:23]
	v_add_f32_e32 v72, v94, v98
	v_add_f32_e32 v70, v70, v75
	s_waitcnt vmcnt(6)
	v_pk_mul_f32 v[74:75], v[8:9], v[8:9]
	s_waitcnt lgkmcnt(0)
	v_add_f32_e32 v69, v69, v103
	v_add_f32_e32 v72, v72, v99
	v_add_f32_e32 v71, v71, v104
	v_add_f32_e32 v74, v74, v75
	ds_bpermute_b32 v75, v61, v69
	v_pk_mul_f32 v[106:107], v[16:17], v[16:17]
	v_add_f32_e32 v70, v70, v72
	v_add_f32_e32 v71, v71, v105
	v_pk_mul_f32 v[108:109], v[18:19], v[18:19]
	v_add_f32_e32 v70, v70, v71
	v_add_f32_e32 v71, v106, v107
	v_add_f32_e32 v71, v71, v108
	v_add_f32_e32 v71, v71, v109
	v_add_f32_e32 v102, v70, v71
	v_pk_mul_f32 v[70:71], v[12:13], v[12:13]
	s_waitcnt lgkmcnt(0)
	v_add_f32_e32 v69, v69, v75
	v_add_f32_e32 v70, v70, v71
	ds_bpermute_b32 v71, v62, v69
	v_pk_mul_f32 v[72:73], v[14:15], v[14:15]
	v_pk_mul_f32 v[92:93], v[10:11], v[10:11]
	s_waitcnt vmcnt(5)
	v_pk_mul_f32 v[94:95], v[4:5], v[4:5]
	v_pk_mul_f32 v[96:97], v[6:7], v[6:7]
	s_waitcnt lgkmcnt(0)
	v_add_f32_e32 v69, v69, v71
	v_add_f32_e32 v74, v74, v92
	v_add_f32_e32 v70, v70, v72
	v_add_f32_e32 v72, v94, v95
	ds_bpermute_b32 v71, v63, v69
	v_add_f32_e32 v74, v74, v93
	v_add_f32_e32 v70, v70, v73
	v_add_f32_e32 v72, v72, v96
	s_waitcnt vmcnt(4)
	v_pk_mul_f32 v[98:99], v[0:1], v[0:1]
	v_add_f32_e32 v70, v70, v74
	v_add_f32_e32 v72, v72, v97
	v_pk_mul_f32 v[100:101], v[2:3], v[2:3]
	v_add_f32_e32 v96, v70, v72
	v_add_f32_e32 v70, v98, v99
	s_waitcnt vmcnt(3)
	v_mov_b32_e32 v92, v77
	s_waitcnt vmcnt(2)
	v_mov_b32_e32 v93, v81
	v_add_f32_e32 v70, v70, v100
	v_mov_b32_e32 v74, v76
	v_mov_b32_e32 v75, v80
	v_pk_mul_f32 v[92:93], v[92:93], v[92:93]
	v_add_f32_e32 v97, v70, v101
	s_waitcnt lgkmcnt(0)
	v_add_f32_e32 v69, v69, v71
	v_mov_b32_e32 v70, v78
	v_mov_b32_e32 v71, v82
	v_pk_fma_f32 v[74:75], v[74:75], v[74:75], v[92:93]
	s_waitcnt vmcnt(1)
	v_mov_b32_e32 v94, v85
	s_waitcnt vmcnt(0)
	v_mov_b32_e32 v95, v89
	v_mov_b32_e32 v72, v79
	v_mov_b32_e32 v73, v83
	v_pk_fma_f32 v[70:71], v[70:71], v[70:71], v[74:75]
	v_mov_b32_e32 v92, v84
	v_mov_b32_e32 v93, v88
	v_pk_mul_f32 v[94:95], v[94:95], v[94:95]
	v_pk_fma_f32 v[70:71], v[72:73], v[72:73], v[70:71]
	v_mov_b32_e32 v72, v86
	v_mov_b32_e32 v73, v90
	v_pk_fma_f32 v[92:93], v[92:93], v[92:93], v[94:95]
	v_mov_b32_e32 v74, v87
	v_mov_b32_e32 v75, v91
	v_pk_fma_f32 v[72:73], v[72:73], v[72:73], v[92:93]
	v_add_f32_e32 v70, v70, v71
	v_pk_fma_f32 v[72:73], v[74:75], v[74:75], v[72:73]
	ds_bpermute_b32 v74, v60, v102
	v_add_f32_e32 v70, v70, v72
	v_add_f32_e32 v70, v70, v73
	ds_bpermute_b32 v71, v60, v70
	ds_bpermute_b32 v98, v64, v69
	s_waitcnt lgkmcnt(2)
	v_add_f32_e32 v74, v102, v74
	ds_bpermute_b32 v75, v61, v74
	v_add_f32_e32 v72, v96, v97
	s_waitcnt lgkmcnt(2)
	v_add_f32_e32 v70, v70, v71
	ds_bpermute_b32 v71, v61, v70
	s_waitcnt lgkmcnt(2)
	v_add_f32_e32 v73, v69, v98
	ds_bpermute_b32 v69, v60, v72
	s_waitcnt lgkmcnt(2)
	v_add_f32_e32 v74, v74, v75
	ds_bpermute_b32 v75, v62, v74
	s_waitcnt lgkmcnt(2)
	v_add_f32_e32 v70, v70, v71
	ds_bpermute_b32 v71, v62, v70
	s_waitcnt lgkmcnt(2)
	v_add_f32_e32 v69, v72, v69
	ds_bpermute_b32 v72, v61, v69
	s_waitcnt lgkmcnt(2)
	v_add_f32_e32 v74, v74, v75
	ds_bpermute_b32 v75, v63, v74
	s_waitcnt lgkmcnt(2)
	v_add_f32_e32 v70, v70, v71
	ds_bpermute_b32 v71, v63, v70
	s_waitcnt lgkmcnt(2)
	v_add_f32_e32 v69, v69, v72
	ds_bpermute_b32 v72, v62, v69
	s_waitcnt lgkmcnt(2)
	v_add_f32_e32 v75, v74, v75
	ds_bpermute_b32 v92, v64, v75
	s_waitcnt lgkmcnt(2)
	v_add_f32_e32 v70, v70, v71
	ds_bpermute_b32 v71, v64, v70
	s_waitcnt lgkmcnt(2)
	v_add_f32_e32 v69, v69, v72
	ds_bpermute_b32 v72, v63, v69
	ds_bpermute_b32 v74, v65, v73
	s_waitcnt lgkmcnt(2)
	v_add_f32_e32 v70, v70, v71
	ds_bpermute_b32 v94, v65, v70
	v_add_f32_e32 v71, v75, v92
	s_waitcnt lgkmcnt(2)
	v_add_f32_e32 v69, v69, v72
	ds_bpermute_b32 v93, v64, v69
	ds_bpermute_b32 v72, v65, v71
	s_waitcnt lgkmcnt(2)
	v_add_f32_e32 v70, v70, v94
	v_fmamk_f32 v70, v70, 0x3a800000, v67
	v_mul_f32_e32 v75, 0x4b800000, v70
	v_cmp_gt_f32_e64 s[8:9], s18, v70
	s_waitcnt lgkmcnt(1)
	v_add_f32_e32 v69, v69, v93
	v_cndmask_b32_e64 v70, v70, v75, s[8:9]
	v_rsq_f32_e32 v75, v70
	ds_bpermute_b32 v70, v65, v69
	v_mul_f32_e32 v92, 0x45800000, v75
	v_cndmask_b32_e64 v92, v75, v92, s[8:9]
	v_pk_mul_f32 v[76:77], v[76:77], v[92:93] op_sel_hi:[1,0]
	v_pk_mul_f32 v[78:79], v[78:79], v[92:93] op_sel_hi:[1,0]
	v_cvt_pk_bf16_f32 v76, v76, v77
	v_cvt_pk_bf16_f32 v77, v78, v79
	global_store_dwordx2 v[58:59], v[76:77], off
	v_pk_mul_f32 v[76:77], v[80:81], v[92:93] op_sel_hi:[1,0]
	v_pk_mul_f32 v[78:79], v[82:83], v[92:93] op_sel_hi:[1,0]
	v_cvt_pk_bf16_f32 v76, v76, v77
	v_cvt_pk_bf16_f32 v77, v78, v79
	global_store_dwordx2 v[58:59], v[76:77], off offset:512
	v_pk_mul_f32 v[76:77], v[84:85], v[92:93] op_sel_hi:[1,0]
	v_pk_mul_f32 v[78:79], v[86:87], v[92:93] op_sel_hi:[1,0]
	v_cvt_pk_bf16_f32 v76, v76, v77
	v_cvt_pk_bf16_f32 v77, v78, v79
	global_store_dwordx2 v[58:59], v[76:77], off offset:1024
	v_pk_mul_f32 v[76:77], v[88:89], v[92:93] op_sel_hi:[1,0]
	v_pk_mul_f32 v[78:79], v[90:91], v[92:93] op_sel_hi:[1,0]
	v_cvt_pk_bf16_f32 v76, v76, v77
	v_cvt_pk_bf16_f32 v77, v78, v79
	global_store_dwordx2 v[58:59], v[76:77], off offset:1536
	s_and_saveexec_b64 s[8:9], s[6:7]
	s_cbranch_execnz .LBB0_871
	s_or_b64 exec, exec, s[8:9]
	s_and_saveexec_b64 s[6:7], s[0:1]
	s_cbranch_execnz .LBB0_872

.LBB0_1423:
	v_add_u32_e32 v0, s16, v58
	v_cmp_gt_i32_e64 s[6:7], s3, v0
	v_lshrrev_b32_e32 v69, 3, v58
	v_and_b32_e32 v59, 0x700, v66
	v_cndmask_b32_e64 v1, v58, v0, s[6:7]
	v_lshlrev_b32_e32 v2, 5, v1
	v_lshrrev_b32_e32 v3, 3, v1
	v_and_b32_e32 v2, 0x700, v2
	v_and_b32_e32 v3, 0xf8, v3
	v_and_b32_e32 v4, 0xfffff807, v1
	v_or3_b32 v2, v2, v4, v3
	v_cndmask_b32_e32 v56, v1, v2, vcc
	v_add_u32_e32 v2, s16, v0
	v_cmp_gt_i32_e64 s[0:1], s3, v2
	v_ashrrev_i32_e32 v57, 31, v56
	v_add_u32_e32 v68, s16, v2
	v_cndmask_b32_e64 v3, v58, v2, s[0:1]
	v_lshlrev_b32_e32 v0, 5, v3
	v_and_b32_e32 v4, 0x700, v0
	v_lshlrev_b64 v[0:1], 12, v[56:57]
	v_lshl_add_u64 v[0:1], v[50:51], 0, v[0:1]
	v_lshrrev_b32_e32 v5, 3, v3
	global_load_dwordx4 v[44:47], v[0:1], off nt
	global_load_dwordx4 v[40:43], v[0:1], off offset:1024 nt
	v_and_b32_e32 v5, 0xf8, v5
	v_and_b32_e32 v6, 0xfffff807, v3
	global_load_dwordx4 v[36:39], v[0:1], off offset:2048 nt
	global_load_dwordx4 v[32:35], v[0:1], off offset:3072 nt
	v_or3_b32 v0, v4, v6, v5
	v_cndmask_b32_e32 v54, v3, v0, vcc
	v_ashrrev_i32_e32 v55, 31, v54
	v_lshlrev_b64 v[0:1], 12, v[54:55]
	v_lshl_add_u64 v[0:1], v[50:51], 0, v[0:1]
	v_cmp_gt_i32_e64 s[4:5], s3, v68
	global_load_dwordx4 v[28:31], v[0:1], off nt
	global_load_dwordx4 v[24:27], v[0:1], off offset:1024 nt
	global_load_dwordx4 v[20:23], v[0:1], off offset:2048 nt
	global_load_dwordx4 v[16:19], v[0:1], off offset:3072 nt
	v_cndmask_b32_e64 v0, v58, v68, s[4:5]
	v_lshlrev_b32_e32 v1, 5, v0
	v_lshrrev_b32_e32 v2, 3, v0
	v_and_b32_e32 v3, 0xfffff807, v0
	v_and_b32_e32 v1, 0x700, v1
	v_and_b32_e32 v2, 0xf8, v2
	v_or3_b32 v1, v1, v3, v2
	v_cndmask_b32_e32 v52, v0, v1, vcc
	v_ashrrev_i32_e32 v53, 31, v52
	v_lshlrev_b64 v[0:1], 12, v[52:53]
	s_waitcnt lgkmcnt(0)
	v_lshl_add_u64 v[70:71], v[50:51], 0, v[0:1]
	global_load_dwordx4 v[12:15], v[70:71], off nt
	global_load_dwordx4 v[8:11], v[70:71], off offset:1024 nt
	global_load_dwordx4 v[4:7], v[70:71], off offset:2048 nt
	global_load_dwordx4 v[0:3], v[70:71], off offset:3072 nt
	v_and_b32_e32 v70, 0xfffff807, v58
	v_and_b32_e32 v69, 0xf8, v69
	v_or3_b32 v59, v59, v70, v69
	v_cndmask_b32_e32 v58, v58, v59, vcc
	v_ashrrev_i32_e32 v59, 31, v58
	v_lshlrev_b64 v[70:71], 12, v[58:59]
	v_lshl_add_u64 v[70:71], v[50:51], 0, v[70:71]
	global_load_dwordx4 v[76:79], v[70:71], off nt
	global_load_dwordx4 v[80:83], v[70:71], off offset:1024 nt
	global_load_dwordx4 v[84:87], v[70:71], off offset:2048 nt
	global_load_dwordx4 v[88:91], v[70:71], off offset:3072 nt
	v_lshlrev_b64 v[58:59], 11, v[58:59]
	v_lshl_add_u64 v[58:59], v[48:49], 0, v[58:59]
	s_waitcnt vmcnt(15)
	v_pk_mul_f32 v[70:71], v[44:45], v[44:45]
	s_waitcnt vmcnt(14)
	v_pk_mul_f32 v[74:75], v[40:41], v[40:41]
	v_pk_mul_f32 v[72:73], v[46:47], v[46:47]
	v_pk_mul_f32 v[92:93], v[42:43], v[42:43]
	s_waitcnt vmcnt(13)
	v_pk_mul_f32 v[94:95], v[36:37], v[36:37]
	v_add_f32_e32 v69, v74, v75
	v_add_f32_e32 v110, v70, v71
	v_pk_mul_f32 v[96:97], v[38:39], v[38:39]
	s_waitcnt vmcnt(12)
	v_pk_mul_f32 v[98:99], v[32:33], v[32:33]
	v_add_f32_e32 v111, v94, v95
	v_add_f32_e32 v69, v69, v92
	v_add_f32_e32 v72, v110, v72
	v_pk_mul_f32 v[100:101], v[34:35], v[34:35]
	v_add_f32_e32 v112, v98, v99
	v_add_f32_e32 v92, v111, v96
	v_add_f32_e32 v69, v69, v93
	v_add_f32_e32 v72, v72, v73
	v_add_f32_e32 v96, v112, v100
	v_add_f32_e32 v73, v92, v97
	v_add_f32_e32 v69, v72, v69
	v_add_f32_e32 v92, v96, v101
	v_add_f32_e32 v69, v69, v73
	s_waitcnt vmcnt(11)
	v_pk_mul_f32 v[70:71], v[28:29], v[28:29]
	s_waitcnt vmcnt(9)
	v_pk_mul_f32 v[102:103], v[20:21], v[20:21]
	v_add_f32_e32 v69, v69, v92
	v_add_f32_e32 v70, v70, v71
	v_add_f32_e32 v71, v102, v103
	ds_bpermute_b32 v103, v60, v69
	v_pk_mul_f32 v[74:75], v[30:31], v[30:31]
	v_pk_mul_f32 v[94:95], v[24:25], v[24:25]
	v_pk_mul_f32 v[98:99], v[26:27], v[26:27]
	v_add_f32_e32 v94, v94, v95
	v_add_f32_e32 v70, v70, v74
	v_pk_mul_f32 v[104:105], v[22:23], v[22:23]
	v_add_f32_e32 v72, v94, v98
	v_add_f32_e32 v70, v70, v75
	s_waitcnt vmcnt(6)
	v_pk_mul_f32 v[74:75], v[8:9], v[8:9]
	s_waitcnt lgkmcnt(0)
	v_add_f32_e32 v69, v69, v103
	v_add_f32_e32 v72, v72, v99
	v_add_f32_e32 v71, v71, v104
	v_add_f32_e32 v74, v74, v75
	ds_bpermute_b32 v75, v61, v69
	v_pk_mul_f32 v[106:107], v[16:17], v[16:17]
	v_add_f32_e32 v70, v70, v72
	v_add_f32_e32 v71, v71, v105
	v_pk_mul_f32 v[108:109], v[18:19], v[18:19]
	v_add_f32_e32 v70, v70, v71
	v_add_f32_e32 v71, v106, v107
	v_add_f32_e32 v71, v71, v108
	v_add_f32_e32 v71, v71, v109
	v_add_f32_e32 v102, v70, v71
	v_pk_mul_f32 v[70:71], v[12:13], v[12:13]
	s_waitcnt lgkmcnt(0)
	v_add_f32_e32 v69, v69, v75
	v_add_f32_e32 v70, v70, v71
	ds_bpermute_b32 v71, v62, v69
	v_pk_mul_f32 v[72:73], v[14:15], v[14:15]
	v_pk_mul_f32 v[92:93], v[10:11], v[10:11]
	s_waitcnt vmcnt(5)
	v_pk_mul_f32 v[94:95], v[4:5], v[4:5]
	v_pk_mul_f32 v[96:97], v[6:7], v[6:7]
	s_waitcnt lgkmcnt(0)
	v_add_f32_e32 v69, v69, v71
	v_add_f32_e32 v74, v74, v92
	v_add_f32_e32 v70, v70, v72
	v_add_f32_e32 v72, v94, v95
	ds_bpermute_b32 v71, v63, v69
	v_add_f32_e32 v74, v74, v93
	v_add_f32_e32 v70, v70, v73
	v_add_f32_e32 v72, v72, v96
	s_waitcnt vmcnt(4)
	v_pk_mul_f32 v[98:99], v[0:1], v[0:1]
	v_add_f32_e32 v70, v70, v74
	v_add_f32_e32 v72, v72, v97
	v_pk_mul_f32 v[100:101], v[2:3], v[2:3]
	v_add_f32_e32 v96, v70, v72
	v_add_f32_e32 v70, v98, v99
	s_waitcnt vmcnt(3)
	v_mov_b32_e32 v92, v77
	s_waitcnt vmcnt(2)
	v_mov_b32_e32 v93, v81
	v_add_f32_e32 v70, v70, v100
	v_mov_b32_e32 v74, v76
	v_mov_b32_e32 v75, v80
	v_pk_mul_f32 v[92:93], v[92:93], v[92:93]
	v_add_f32_e32 v97, v70, v101
	s_waitcnt lgkmcnt(0)
	v_add_f32_e32 v69, v69, v71
	v_mov_b32_e32 v70, v78
	v_mov_b32_e32 v71, v82
	v_pk_fma_f32 v[74:75], v[74:75], v[74:75], v[92:93]
	s_waitcnt vmcnt(1)
	v_mov_b32_e32 v94, v85
	s_waitcnt vmcnt(0)
	v_mov_b32_e32 v95, v89
	v_mov_b32_e32 v72, v79
	v_mov_b32_e32 v73, v83
	v_pk_fma_f32 v[70:71], v[70:71], v[70:71], v[74:75]
	v_mov_b32_e32 v92, v84
	v_mov_b32_e32 v93, v88
	v_pk_mul_f32 v[94:95], v[94:95], v[94:95]
	v_pk_fma_f32 v[70:71], v[72:73], v[72:73], v[70:71]
	v_mov_b32_e32 v72, v86
	v_mov_b32_e32 v73, v90
	v_pk_fma_f32 v[92:93], v[92:93], v[92:93], v[94:95]
	v_mov_b32_e32 v74, v87
	v_mov_b32_e32 v75, v91
	v_pk_fma_f32 v[72:73], v[72:73], v[72:73], v[92:93]
	v_add_f32_e32 v70, v70, v71
	v_pk_fma_f32 v[72:73], v[74:75], v[74:75], v[72:73]
	ds_bpermute_b32 v74, v60, v102
	v_add_f32_e32 v70, v70, v72
	v_add_f32_e32 v70, v70, v73
	ds_bpermute_b32 v71, v60, v70
	ds_bpermute_b32 v98, v64, v69
	s_waitcnt lgkmcnt(2)
	v_add_f32_e32 v74, v102, v74
	ds_bpermute_b32 v75, v61, v74
	v_add_f32_e32 v72, v96, v97
	s_waitcnt lgkmcnt(2)
	v_add_f32_e32 v70, v70, v71
	ds_bpermute_b32 v71, v61, v70
	s_waitcnt lgkmcnt(2)
	v_add_f32_e32 v73, v69, v98
	ds_bpermute_b32 v69, v60, v72
	s_waitcnt lgkmcnt(2)
	v_add_f32_e32 v74, v74, v75
	ds_bpermute_b32 v75, v62, v74
	s_waitcnt lgkmcnt(2)
	v_add_f32_e32 v70, v70, v71
	ds_bpermute_b32 v71, v62, v70
	s_waitcnt lgkmcnt(2)
	v_add_f32_e32 v69, v72, v69
	ds_bpermute_b32 v72, v61, v69
	s_waitcnt lgkmcnt(2)
	v_add_f32_e32 v74, v74, v75
	ds_bpermute_b32 v75, v63, v74
	s_waitcnt lgkmcnt(2)
	v_add_f32_e32 v70, v70, v71
	ds_bpermute_b32 v71, v63, v70
	s_waitcnt lgkmcnt(2)
	v_add_f32_e32 v69, v69, v72
	ds_bpermute_b32 v72, v62, v69
	s_waitcnt lgkmcnt(2)
	v_add_f32_e32 v75, v74, v75
	ds_bpermute_b32 v92, v64, v75
	s_waitcnt lgkmcnt(2)
	v_add_f32_e32 v70, v70, v71
	ds_bpermute_b32 v71, v64, v70
	s_waitcnt lgkmcnt(2)
	v_add_f32_e32 v69, v69, v72
	ds_bpermute_b32 v72, v63, v69
	ds_bpermute_b32 v74, v65, v73
	s_waitcnt lgkmcnt(2)
	v_add_f32_e32 v70, v70, v71
	ds_bpermute_b32 v94, v65, v70
	v_add_f32_e32 v71, v75, v92
	s_waitcnt lgkmcnt(2)
	v_add_f32_e32 v69, v69, v72
	ds_bpermute_b32 v93, v64, v69
	ds_bpermute_b32 v72, v65, v71
	s_waitcnt lgkmcnt(2)
	v_add_f32_e32 v70, v70, v94
	v_fmamk_f32 v70, v70, 0x3a800000, v67
	v_mul_f32_e32 v75, 0x4b800000, v70
	v_cmp_gt_f32_e64 s[8:9], s18, v70
	s_waitcnt lgkmcnt(1)
	v_add_f32_e32 v69, v69, v93
	v_cndmask_b32_e64 v70, v70, v75, s[8:9]
	v_rsq_f32_e32 v75, v70
	ds_bpermute_b32 v70, v65, v69
	v_mul_f32_e32 v92, 0x45800000, v75
	v_cndmask_b32_e64 v92, v75, v92, s[8:9]
	v_pk_mul_f32 v[76:77], v[76:77], v[92:93] op_sel_hi:[1,0]
	v_pk_mul_f32 v[78:79], v[78:79], v[92:93] op_sel_hi:[1,0]
	v_cvt_pk_bf16_f32 v76, v76, v77
	v_cvt_pk_bf16_f32 v77, v78, v79
	global_store_dwordx2 v[58:59], v[76:77], off
	v_pk_mul_f32 v[76:77], v[80:81], v[92:93] op_sel_hi:[1,0]
	v_pk_mul_f32 v[78:79], v[82:83], v[92:93] op_sel_hi:[1,0]
	v_cvt_pk_bf16_f32 v76, v76, v77
	v_cvt_pk_bf16_f32 v77, v78, v79
	global_store_dwordx2 v[58:59], v[76:77], off offset:512
	v_pk_mul_f32 v[76:77], v[84:85], v[92:93] op_sel_hi:[1,0]
	v_pk_mul_f32 v[78:79], v[86:87], v[92:93] op_sel_hi:[1,0]
	v_cvt_pk_bf16_f32 v76, v76, v77
	v_cvt_pk_bf16_f32 v77, v78, v79
	global_store_dwordx2 v[58:59], v[76:77], off offset:1024
	v_pk_mul_f32 v[76:77], v[88:89], v[92:93] op_sel_hi:[1,0]
	v_pk_mul_f32 v[78:79], v[90:91], v[92:93] op_sel_hi:[1,0]
	v_cvt_pk_bf16_f32 v76, v76, v77
	v_cvt_pk_bf16_f32 v77, v78, v79
	global_store_dwordx2 v[58:59], v[76:77], off offset:1536
	s_and_saveexec_b64 s[8:9], s[6:7]
	s_cbranch_execnz .LBB0_1426
	s_or_b64 exec, exec, s[8:9]
	s_and_saveexec_b64 s[6:7], s[0:1]
	s_cbranch_execnz .LBB0_1427
